# combo7 + down1 and down2 first K-iteration peeled with SrcC=0 (zeroing removed for 52 of 62 tiles)
# speedup vs baseline: 1.0176x; 1.0057x over previous
; #define PG8_STAGE(bufoff, gbase, voff) do { _Pragma("unroll") for (int _i = 0; _i < 2; ++_i) \
;         __builtin_amdgcn_global_load_lds((const unsigned*)((const char*)(gbase) + (voff)[_i]), (PG8_LAS unsigned*)(lds + (bufoff) + ldsw + _i * 8192), 16, 0, 0); } while (0)
; #define PG8_LDA(dst, b, h) do { _Pragma("unroll") for (int m = 0; m < 4; ++m) _Pragma("unroll") for (int k = 0; k < 2; ++k) dst[m][k] = *(const PG8_LAS bf16x8*)(lds + PG8_SA(b, h) + aoff + m * 2048 + k * 1024); } while (0)
; #define PG8_LDB(dst, b, h) do { _Pragma("unroll") for (int n = 0; n < 2; ++n) _Pragma("unroll") for (int k = 0; k < 2; ++k) dst[n][k] = *(const PG8_LAS bf16x8*)(lds + PG8_SB(b, h) + boff + n * 2048 + k * 1024); } while (0)
; #define PG8_WAIT_V(n) asm volatile("s_waitcnt vmcnt(" #n ")" ::: "memory")
; template <class Epi, class Sched, bool ALIGN_EPI = false, bool SP2 = false>
; __device__ __forceinline__ void gemm_phase(PG8_LAS unsigned char* lds, const Gemm g, const Sched& S, const Epi& E, const int tid) {
;     ...
;         const char* nA = has_next ? (const char*)g.A + (size_t)nxt.pm * tstep : cA; const char* nB = has_next ? (const char*)g.Bt + (size_t)nxt.pn * tstep : cB;
;         for (int t = 0; t < nt; t += 2) {
;             const bool last = (t == nt - 2);
;             const char* a1 = cA + (size_t)(t + 1) * kstep;
;             const char* a2 = last ? nA : cA + (size_t)(t + 2) * kstep; const char* b2 = last ? nB : cB + (size_t)(t + 2) * kstep;
;             const char* a3 = a2 + kstep; const char* b3 = b2 + kstep;
;             if (last && has_next) S.a_ready(nxt);
;             if (last) E.prefetch(lds + EPI_LDS_OFF + wid * 1024, cur, wr, wc, lane);
;             if constexpr (SP2) {
;             PG8_LDB(B0, 0, 0); PG8_LDB(B1, 0, 1); PG8_SCHED; PG8_LDA(At, 0, 0); PG8_STAGE(PG8_SA(1, 1), a1 + hstep, voffA);
;             PG8_WAIT_V(8); PG8_WAIT_L(0); PG8_BAR; PG8_MMA(0, 0, At, B0); PG8_MMA(0, 1, At, B1); PG8_BAR; PG8_SCHED;
;             PG8_LDA(At, 0, 1); PG8_STAGE(PG8_SB(0, 0), b2, voffB); PG8_STAGE(PG8_SB(0, 1), b2 + hstep, voffB); PG8_STAGE(PG8_SA(0, 0), a2, voffA);
;     __device__ __forceinline__ void prefetch(LAS unsigned char* sl, const pg8::Unit& u, int wr, int wc, int lane) const {
;     ...
;         const int col = u.pn * pg8::BM + wc * 32 + (lane & 31) + (lane >> 5) * pg8::HALF; const size_t bo = (size_t)(u.pm / (SEQ / 256)) * MODW;
.LBB0_41:
	s_ashr_i32 s3, s53, 31
	s_lshr_b32 s3, s3, 27
	s_add_i32 s3, s53, s3
	s_lshl_b32 s54, s20, 8
	s_ashr_i32 s3, s3, 5
	v_or_b32_e32 v132, s54, v226
	s_add_u32 s55, s18, 0x100
	s_mul_hi_i32 s50, s3, 0x12000
	s_mul_i32 s51, s3, 0x12000
	v_ashrrev_i32_e32 v133, 31, v132
	s_addc_u32 s74, s19, 0
	s_mov_b32 s75, -2
	s_waitcnt vmcnt(0)
	s_mov_b64 s[20:21], 0
.Ld2_peel:
	s_add_u32 s18, s16, 0x100
	s_addc_u32 s19, s17, 0
	s_and_b64 s[20:21], s[20:21], exec
	s_cselect_b32 s23, s9, s19
	s_cselect_b32 s22, s8, s18
	s_cselect_b32 s21, s15, s74
	s_cselect_b32 s20, s14, s55
	s_add_i32 s3, 0, 0x10000
	s_add_i32 s42, 0, 0x14000
	v_add_u32_e32 v146, s3, v224
	v_add_u32_e32 v162, s42, v224
	ds_read_b128 v[134:137], v146
	ds_read_b128 v[138:141], v146 offset:1024
	ds_read_b128 v[142:145], v146 offset:2048
	ds_read_b128 v[146:149], v146 offset:3072
	ds_read_b128 v[150:153], v162
	ds_read_b128 v[154:157], v162 offset:1024
	ds_read_b128 v[158:161], v162 offset:2048
	ds_read_b128 v[172:175], v162 offset:3072
	v_lshl_add_u64 v[162:163], s[16:17], 0, v[168:169]
	s_add_i32 m0, s27, 0xc000
	ds_read_b128 v[176:179], v228
	ds_read_b128 v[180:183], v228 offset:1024
	ds_read_b128 v[186:189], v228 offset:2048
	ds_read_b128 v[190:193], v228 offset:3072
	ds_read_b128 v[194:197], v228 offset:4096
	ds_read_b128 v[198:201], v228 offset:5120
	ds_read_b128 v[202:205], v228 offset:6144
	ds_read_b128 v[206:209], v228 offset:7168
	global_load_lds_dwordx4 v[162:163], off
	v_lshl_add_u64 v[162:163], s[16:17], 0, v[170:171]
	s_add_i32 m0, s27, 0xe000
	s_nop 0
	global_load_lds_dwordx4 v[162:163], off
	s_waitcnt vmcnt(8)
	s_waitcnt lgkmcnt(0)
	s_setprio 1
	s_barrier
	v_mfma_f32_16x16x32_bf16 v[128:131], v[134:137], v[176:179], 0
	v_mfma_f32_16x16x32_bf16 v[124:127], v[142:145], v[176:179], 0
	v_mfma_f32_16x16x32_bf16 v[112:115], v[134:137], v[186:189], 0
	v_mfma_f32_16x16x32_bf16 v[108:111], v[142:145], v[186:189], 0
	v_mfma_f32_16x16x32_bf16 v[96:99], v[134:137], v[194:197], 0
	v_mfma_f32_16x16x32_bf16 v[92:95], v[142:145], v[194:197], 0
	v_mfma_f32_16x16x32_bf16 v[80:83], v[134:137], v[202:205], 0
	v_mfma_f32_16x16x32_bf16 v[76:79], v[142:145], v[202:205], 0
	v_mfma_f32_16x16x32_bf16 v[128:131], v[138:141], v[180:183], v[128:131]
	v_mfma_f32_16x16x32_bf16 v[124:127], v[146:149], v[180:183], v[124:127]
	v_mfma_f32_16x16x32_bf16 v[112:115], v[138:141], v[190:193], v[112:115]
	v_mfma_f32_16x16x32_bf16 v[108:111], v[146:149], v[190:193], v[108:111]
	v_mfma_f32_16x16x32_bf16 v[96:99], v[138:141], v[198:201], v[96:99]
	v_mfma_f32_16x16x32_bf16 v[92:95], v[146:149], v[198:201], v[92:95]
	v_mfma_f32_16x16x32_bf16 v[80:83], v[138:141], v[206:209], v[80:83]
	v_mfma_f32_16x16x32_bf16 v[76:79], v[146:149], v[206:209], v[76:79]
	s_setprio 0
	s_setprio 1
	v_mfma_f32_16x16x32_bf16 v[120:123], v[150:153], v[176:179], 0
	v_mfma_f32_16x16x32_bf16 v[116:119], v[158:161], v[176:179], 0
	v_mfma_f32_16x16x32_bf16 v[104:107], v[150:153], v[186:189], 0
	v_mfma_f32_16x16x32_bf16 v[100:103], v[158:161], v[186:189], 0
	v_mfma_f32_16x16x32_bf16 v[88:91], v[150:153], v[194:197], 0
	v_mfma_f32_16x16x32_bf16 v[84:87], v[158:161], v[194:197], 0
	v_mfma_f32_16x16x32_bf16 v[72:75], v[150:153], v[202:205], 0
	v_mfma_f32_16x16x32_bf16 v[68:71], v[158:161], v[202:205], 0
	v_mfma_f32_16x16x32_bf16 v[120:123], v[154:157], v[180:183], v[120:123]
	v_mfma_f32_16x16x32_bf16 v[116:119], v[172:175], v[180:183], v[116:119]
	v_mfma_f32_16x16x32_bf16 v[104:107], v[154:157], v[190:193], v[104:107]
	v_mfma_f32_16x16x32_bf16 v[100:103], v[172:175], v[190:193], v[100:103]
	v_mfma_f32_16x16x32_bf16 v[88:91], v[154:157], v[198:201], v[88:91]
	v_mfma_f32_16x16x32_bf16 v[84:87], v[172:175], v[198:201], v[84:87]
	v_mfma_f32_16x16x32_bf16 v[72:75], v[154:157], v[206:209], v[72:75]
	v_mfma_f32_16x16x32_bf16 v[68:71], v[172:175], v[206:209], v[68:71]
	s_setprio 0
	s_barrier
	s_add_i32 s3, s3, s26
	v_lshl_add_u64 v[162:163], s[20:21], 0, v[2:3]
	s_mov_b32 m0, s3
	ds_read_b128 v[176:179], v228 offset:16384
	ds_read_b128 v[180:183], v228 offset:17408
	ds_read_b128 v[186:189], v228 offset:18432
	ds_read_b128 v[190:193], v228 offset:19456
	ds_read_b128 v[194:197], v228 offset:20480
	ds_read_b128 v[198:201], v228 offset:21504
	ds_read_b128 v[202:205], v228 offset:22528
	ds_read_b128 v[206:209], v228 offset:23552
	global_load_lds_dwordx4 v[162:163], off
	s_add_i32 m0, s3, 0x2000
	s_add_u32 s16, s20, 0x160000
	v_lshl_add_u64 v[210:211], s[20:21], 0, v[166:167]
	s_addc_u32 s17, s21, 0
	s_add_i32 s3, s42, s26
	global_load_lds_dwordx4 v[210:211], off
	v_lshl_add_u64 v[212:213], s[16:17], 0, v[2:3]
	s_mov_b32 m0, s3
	v_lshl_add_u64 v[214:215], s[22:23], 0, v[164:165]
	global_load_lds_dwordx4 v[212:213], off
	v_lshl_add_u64 v[212:213], s[16:17], 0, v[166:167]
	s_add_i32 m0, s3, 0x2000
	s_nop 0
	global_load_lds_dwordx4 v[212:213], off
	v_lshl_add_u64 v[212:213], s[22:23], 0, v[0:1]
	s_mov_b32 m0, s27
	s_nop 0
	global_load_lds_dwordx4 v[212:213], off
	s_mov_b32 m0, s28
	s_nop 0
	global_load_lds_dwordx4 v[214:215], off
	s_waitcnt vmcnt(8)
	s_waitcnt lgkmcnt(0)
	s_setprio 1
	s_barrier
; #define PG8_STAGE(bufoff, gbase, voff) do { _Pragma("unroll") for (int _i = 0; _i < 2; ++_i) \
;         __builtin_amdgcn_global_load_lds((const unsigned*)((const char*)(gbase) + (voff)[_i]), (PG8_LAS unsigned*)(lds + (bufoff) + ldsw + _i * 8192), 16, 0, 0); } while (0)
; #define PG8_LDA(dst, b, h) do { _Pragma("unroll") for (int m = 0; m < 4; ++m) _Pragma("unroll") for (int k = 0; k < 2; ++k) dst[m][k] = *(const PG8_LAS bf16x8*)(lds + PG8_SA(b, h) + aoff + m * 2048 + k * 1024); } while (0)
; #define PG8_LDB(dst, b, h) do { _Pragma("unroll") for (int n = 0; n < 2; ++n) _Pragma("unroll") for (int k = 0; k < 2; ++k) dst[n][k] = *(const PG8_LAS bf16x8*)(lds + PG8_SB(b, h) + boff + n * 2048 + k * 1024); } while (0)
; #define PG8_MMA(ai, bj, At, Bt) do { __builtin_amdgcn_s_setprio(1); _Pragma("unroll") for (int m = 0; m < 4; ++m) _Pragma("unroll") for (int n = 0; n < 2; ++n) _Pragma("unroll") for (int k = 0; k < 2; ++k) \
;         acc[ai][bj][m][n] = __builtin_amdgcn_mfma_f32_16x16x32_bf16(Bt[n][k], At[m][k], acc[ai][bj][m][n], 0, 0, 0); __builtin_amdgcn_s_setprio(0); } while (0)
; #define PG8_WAIT_V(n) asm volatile("s_waitcnt vmcnt(" #n ")" ::: "memory")
; #define PG8_WAIT_L(n) asm volatile("s_waitcnt lgkmcnt(" #n ")" ::: "memory")
; #define PG8_BAR __builtin_amdgcn_s_barrier()
; #define PG8_SCHED __builtin_amdgcn_sched_barrier(0)
; template <class Epi, class Sched, bool ALIGN_EPI = false, bool SP2 = false>
; __device__ __forceinline__ void gemm_phase(PG8_LAS unsigned char* lds, const Gemm g, const Sched& S, const Epi& E, const int tid) {
;     ...
;             PG8_WAIT_V(8); PG8_WAIT_L(0); PG8_BAR; PG8_MMA(1, 0, At, B0); PG8_MMA(1, 1, At, B1); PG8_BAR; PG8_SCHED;
;             PG8_LDB(B0, 1, 0); PG8_LDB(B1, 1, 1); PG8_SCHED; PG8_LDA(At, 1, 0); PG8_STAGE(PG8_SA(0, 1), a2 + hstep, voffA);
;             PG8_WAIT_V(8); PG8_WAIT_L(0); PG8_BAR; PG8_MMA(0, 0, At, B0); PG8_MMA(0, 1, At, B1); PG8_BAR; PG8_SCHED;
	v_mfma_f32_16x16x32_bf16 v[64:67], v[134:137], v[176:179], 0
	v_mfma_f32_16x16x32_bf16 v[60:63], v[142:145], v[176:179], 0
	v_mfma_f32_16x16x32_bf16 v[48:51], v[134:137], v[186:189], 0
	v_mfma_f32_16x16x32_bf16 v[44:47], v[142:145], v[186:189], 0
	v_mfma_f32_16x16x32_bf16 v[32:35], v[134:137], v[194:197], 0
	v_mfma_f32_16x16x32_bf16 v[28:31], v[142:145], v[194:197], 0
	v_mfma_f32_16x16x32_bf16 v[16:19], v[134:137], v[202:205], 0
	v_mfma_f32_16x16x32_bf16 v[12:15], v[142:145], v[202:205], 0
	v_mfma_f32_16x16x32_bf16 v[64:67], v[138:141], v[180:183], v[64:67]
	v_mfma_f32_16x16x32_bf16 v[60:63], v[146:149], v[180:183], v[60:63]
	v_mfma_f32_16x16x32_bf16 v[48:51], v[138:141], v[190:193], v[48:51]
	v_mfma_f32_16x16x32_bf16 v[44:47], v[146:149], v[190:193], v[44:47]
	v_mfma_f32_16x16x32_bf16 v[32:35], v[138:141], v[198:201], v[32:35]
	v_mfma_f32_16x16x32_bf16 v[28:31], v[146:149], v[198:201], v[28:31]
	v_mfma_f32_16x16x32_bf16 v[16:19], v[138:141], v[206:209], v[16:19]
	v_mfma_f32_16x16x32_bf16 v[12:15], v[146:149], v[206:209], v[12:15]
	s_setprio 0
	s_setprio 1
	v_mfma_f32_16x16x32_bf16 v[56:59], v[150:153], v[176:179], 0
	v_mfma_f32_16x16x32_bf16 v[52:55], v[158:161], v[176:179], 0
	v_mfma_f32_16x16x32_bf16 v[40:43], v[150:153], v[186:189], 0
	v_mfma_f32_16x16x32_bf16 v[36:39], v[158:161], v[186:189], 0
	v_mfma_f32_16x16x32_bf16 v[24:27], v[150:153], v[194:197], 0
	v_mfma_f32_16x16x32_bf16 v[20:23], v[158:161], v[194:197], 0
	v_mfma_f32_16x16x32_bf16 v[8:11], v[150:153], v[202:205], 0
	v_mfma_f32_16x16x32_bf16 v[4:7], v[158:161], v[202:205], 0
	v_mfma_f32_16x16x32_bf16 v[56:59], v[154:157], v[180:183], v[56:59]
	v_mfma_f32_16x16x32_bf16 v[52:55], v[172:175], v[180:183], v[52:55]
	v_mfma_f32_16x16x32_bf16 v[40:43], v[154:157], v[190:193], v[40:43]
	v_mfma_f32_16x16x32_bf16 v[36:39], v[172:175], v[190:193], v[36:39]
	v_mfma_f32_16x16x32_bf16 v[24:27], v[154:157], v[198:201], v[24:27]
	v_mfma_f32_16x16x32_bf16 v[20:23], v[172:175], v[198:201], v[20:23]
	v_mfma_f32_16x16x32_bf16 v[8:11], v[154:157], v[206:209], v[8:11]
	v_mfma_f32_16x16x32_bf16 v[4:7], v[172:175], v[206:209], v[4:7]
	s_setprio 0
	s_barrier
	s_add_i32 s3, 0, 0x18000
	s_add_i32 s42, 0, 0x1c000
	v_add_u32_e32 v146, s3, v224
	v_add_u32_e32 v172, s42, v224
	ds_read_b128 v[134:137], v146
	ds_read_b128 v[138:141], v146 offset:1024
	ds_read_b128 v[142:145], v146 offset:2048
	ds_read_b128 v[146:149], v146 offset:3072
	ds_read_b128 v[150:153], v172
	ds_read_b128 v[154:157], v172 offset:1024
	ds_read_b128 v[158:161], v172 offset:2048
	ds_read_b128 v[172:175], v172 offset:3072
	s_add_u32 s16, s22, 0x160000
	s_addc_u32 s17, s23, 0
	s_mov_b32 m0, s29
	v_lshl_add_u64 v[216:217], s[16:17], 0, v[0:1]
	ds_read_b128 v[176:179], v228 offset:32768
	ds_read_b128 v[180:183], v228 offset:33792
	ds_read_b128 v[186:189], v228 offset:34816
	ds_read_b128 v[190:193], v228 offset:35840
	ds_read_b128 v[194:197], v228 offset:36864
	ds_read_b128 v[198:201], v228 offset:37888
	ds_read_b128 v[202:205], v228 offset:38912
	ds_read_b128 v[206:209], v228 offset:39936
	global_load_lds_dwordx4 v[216:217], off
	v_lshl_add_u64 v[216:217], s[16:17], 0, v[164:165]
	s_mov_b32 m0, s30
	s_nop 0
	global_load_lds_dwordx4 v[216:217], off
	s_waitcnt vmcnt(8)
	s_waitcnt lgkmcnt(0)
	s_setprio 1
	s_barrier
	v_mfma_f32_16x16x32_bf16 v[128:131], v[134:137], v[176:179], v[128:131]
	v_mfma_f32_16x16x32_bf16 v[124:127], v[142:145], v[176:179], v[124:127]
	v_mfma_f32_16x16x32_bf16 v[112:115], v[134:137], v[186:189], v[112:115]
	v_mfma_f32_16x16x32_bf16 v[108:111], v[142:145], v[186:189], v[108:111]
	v_mfma_f32_16x16x32_bf16 v[96:99], v[134:137], v[194:197], v[96:99]
	v_mfma_f32_16x16x32_bf16 v[92:95], v[142:145], v[194:197], v[92:95]
	v_mfma_f32_16x16x32_bf16 v[80:83], v[134:137], v[202:205], v[80:83]
	v_mfma_f32_16x16x32_bf16 v[76:79], v[142:145], v[202:205], v[76:79]
	v_mfma_f32_16x16x32_bf16 v[128:131], v[138:141], v[180:183], v[128:131]
	v_mfma_f32_16x16x32_bf16 v[124:127], v[146:149], v[180:183], v[124:127]
	v_mfma_f32_16x16x32_bf16 v[112:115], v[138:141], v[190:193], v[112:115]
	v_mfma_f32_16x16x32_bf16 v[108:111], v[146:149], v[190:193], v[108:111]
	v_mfma_f32_16x16x32_bf16 v[96:99], v[138:141], v[198:201], v[96:99]
	v_mfma_f32_16x16x32_bf16 v[92:95], v[146:149], v[198:201], v[92:95]
	v_mfma_f32_16x16x32_bf16 v[80:83], v[138:141], v[206:209], v[80:83]
	v_mfma_f32_16x16x32_bf16 v[76:79], v[146:149], v[206:209], v[76:79]
	s_setprio 0
	s_setprio 1
	v_mfma_f32_16x16x32_bf16 v[120:123], v[150:153], v[176:179], v[120:123]
	v_mfma_f32_16x16x32_bf16 v[116:119], v[158:161], v[176:179], v[116:119]
	v_mfma_f32_16x16x32_bf16 v[104:107], v[150:153], v[186:189], v[104:107]
	v_mfma_f32_16x16x32_bf16 v[100:103], v[158:161], v[186:189], v[100:103]
	v_mfma_f32_16x16x32_bf16 v[88:91], v[150:153], v[194:197], v[88:91]
	v_mfma_f32_16x16x32_bf16 v[84:87], v[158:161], v[194:197], v[84:87]
	v_mfma_f32_16x16x32_bf16 v[72:75], v[150:153], v[202:205], v[72:75]
	v_mfma_f32_16x16x32_bf16 v[68:71], v[158:161], v[202:205], v[68:71]
	v_mfma_f32_16x16x32_bf16 v[120:123], v[154:157], v[180:183], v[120:123]
	v_mfma_f32_16x16x32_bf16 v[116:119], v[172:175], v[180:183], v[116:119]
	v_mfma_f32_16x16x32_bf16 v[104:107], v[154:157], v[190:193], v[104:107]
	v_mfma_f32_16x16x32_bf16 v[100:103], v[172:175], v[190:193], v[100:103]
	v_mfma_f32_16x16x32_bf16 v[88:91], v[154:157], v[198:201], v[88:91]
	v_mfma_f32_16x16x32_bf16 v[84:87], v[172:175], v[198:201], v[84:87]
	v_mfma_f32_16x16x32_bf16 v[72:75], v[154:157], v[206:209], v[72:75]
	v_mfma_f32_16x16x32_bf16 v[68:71], v[172:175], v[206:209], v[68:71]
	s_setprio 0
	s_barrier
; #define PG8_STAGE(bufoff, gbase, voff) do { _Pragma("unroll") for (int _i = 0; _i < 2; ++_i) \
;         __builtin_amdgcn_global_load_lds((const unsigned*)((const char*)(gbase) + (voff)[_i]), (PG8_LAS unsigned*)(lds + (bufoff) + ldsw + _i * 8192), 16, 0, 0); } while (0)
; #define PG8_LDA(dst, b, h) do { _Pragma("unroll") for (int m = 0; m < 4; ++m) _Pragma("unroll") for (int k = 0; k < 2; ++k) dst[m][k] = *(const PG8_LAS bf16x8*)(lds + PG8_SA(b, h) + aoff + m * 2048 + k * 1024); } while (0)
; #define PG8_MMA(ai, bj, At, Bt) do { __builtin_amdgcn_s_setprio(1); _Pragma("unroll") for (int m = 0; m < 4; ++m) _Pragma("unroll") for (int n = 0; n < 2; ++n) _Pragma("unroll") for (int k = 0; k < 2; ++k) \
;         acc[ai][bj][m][n] = __builtin_amdgcn_mfma_f32_16x16x32_bf16(Bt[n][k], At[m][k], acc[ai][bj][m][n], 0, 0, 0); __builtin_amdgcn_s_setprio(0); } while (0)
; #define PG8_WAIT_V(n) asm volatile("s_waitcnt vmcnt(" #n ")" ::: "memory")
; #define PG8_WAIT_L(n) asm volatile("s_waitcnt lgkmcnt(" #n ")" ::: "memory")
; #define PG8_BAR __builtin_amdgcn_s_barrier()
; #define PG8_SCHED __builtin_amdgcn_sched_barrier(0)
; template <class Epi, class Sched, bool ALIGN_EPI = false, bool SP2 = false>
; __device__ __forceinline__ void gemm_phase(PG8_LAS unsigned char* lds, const Gemm g, const Sched& S, const Epi& E, const int tid) {
;     ...
;         for (int t = 0; t < nt; t += 2) {
;     ...
;             PG8_LDA(At, 1, 1); PG8_STAGE(PG8_SB(1, 0), b3, voffB); PG8_STAGE(PG8_SB(1, 1), b3 + hstep, voffB); PG8_STAGE(PG8_SA(1, 0), a3, voffA);
;             PG8_WAIT_V(8); PG8_WAIT_L(0); PG8_BAR; PG8_MMA(1, 0, At, B0); PG8_MMA(1, 1, At, B1); PG8_BAR; PG8_SCHED;
	s_add_i32 s3, s3, s26
	v_lshl_add_u64 v[162:163], v[162:163], 0, s[46:47]
	s_mov_b32 m0, s3
	ds_read_b128 v[176:179], v228 offset:49152
	ds_read_b128 v[180:183], v228 offset:50176
	ds_read_b128 v[186:189], v228 offset:51200
	ds_read_b128 v[190:193], v228 offset:52224
	ds_read_b128 v[194:197], v228 offset:53248
	ds_read_b128 v[198:201], v228 offset:54272
	ds_read_b128 v[202:205], v228 offset:55296
	ds_read_b128 v[206:209], v228 offset:56320
	global_load_lds_dwordx4 v[162:163], off
	s_add_i32 m0, s3, 0x2000
	s_add_u32 s16, s20, 0x160080
	v_lshl_add_u64 v[162:163], v[210:211], 0, s[46:47]
	s_addc_u32 s17, s21, 0
	s_add_i32 s3, s42, s26
	global_load_lds_dwordx4 v[162:163], off
	v_lshl_add_u64 v[162:163], s[16:17], 0, v[2:3]
	s_mov_b32 m0, s3
	s_nop 0
	global_load_lds_dwordx4 v[162:163], off
	v_lshl_add_u64 v[162:163], s[16:17], 0, v[166:167]
	s_add_i32 m0, s3, 0x2000
	s_nop 0
	global_load_lds_dwordx4 v[162:163], off
	v_lshl_add_u64 v[162:163], v[212:213], 0, s[46:47]
	s_mov_b32 m0, s31
	s_nop 0
	global_load_lds_dwordx4 v[162:163], off
	v_lshl_add_u64 v[162:163], v[214:215], 0, s[46:47]
	s_mov_b32 m0, s37
	s_nop 0
	global_load_lds_dwordx4 v[162:163], off
	s_waitcnt vmcnt(8)
	s_waitcnt lgkmcnt(0)
	s_setprio 1
	s_barrier
	v_mfma_f32_16x16x32_bf16 v[64:67], v[134:137], v[176:179], v[64:67]
	v_mfma_f32_16x16x32_bf16 v[60:63], v[142:145], v[176:179], v[60:63]
	v_mfma_f32_16x16x32_bf16 v[48:51], v[134:137], v[186:189], v[48:51]
	v_mfma_f32_16x16x32_bf16 v[44:47], v[142:145], v[186:189], v[44:47]
	v_mfma_f32_16x16x32_bf16 v[32:35], v[134:137], v[194:197], v[32:35]
	v_mfma_f32_16x16x32_bf16 v[28:31], v[142:145], v[194:197], v[28:31]
	v_mfma_f32_16x16x32_bf16 v[16:19], v[134:137], v[202:205], v[16:19]
	v_mfma_f32_16x16x32_bf16 v[12:15], v[142:145], v[202:205], v[12:15]
	v_mfma_f32_16x16x32_bf16 v[64:67], v[138:141], v[180:183], v[64:67]
	v_mfma_f32_16x16x32_bf16 v[60:63], v[146:149], v[180:183], v[60:63]
	v_mfma_f32_16x16x32_bf16 v[48:51], v[138:141], v[190:193], v[48:51]
	v_mfma_f32_16x16x32_bf16 v[44:47], v[146:149], v[190:193], v[44:47]
	v_mfma_f32_16x16x32_bf16 v[32:35], v[138:141], v[198:201], v[32:35]
	v_mfma_f32_16x16x32_bf16 v[28:31], v[146:149], v[198:201], v[28:31]
	v_mfma_f32_16x16x32_bf16 v[16:19], v[138:141], v[206:209], v[16:19]
	v_mfma_f32_16x16x32_bf16 v[12:15], v[146:149], v[206:209], v[12:15]
	s_setprio 0
	s_setprio 1
	v_mfma_f32_16x16x32_bf16 v[56:59], v[150:153], v[176:179], v[56:59]
	v_mfma_f32_16x16x32_bf16 v[52:55], v[158:161], v[176:179], v[52:55]
	v_mfma_f32_16x16x32_bf16 v[40:43], v[150:153], v[186:189], v[40:43]
	v_mfma_f32_16x16x32_bf16 v[36:39], v[158:161], v[186:189], v[36:39]
	v_mfma_f32_16x16x32_bf16 v[24:27], v[150:153], v[194:197], v[24:27]
	v_mfma_f32_16x16x32_bf16 v[20:23], v[158:161], v[194:197], v[20:23]
	v_mfma_f32_16x16x32_bf16 v[8:11], v[150:153], v[202:205], v[8:11]
	v_mfma_f32_16x16x32_bf16 v[4:7], v[158:161], v[202:205], v[4:7]
	v_mfma_f32_16x16x32_bf16 v[56:59], v[154:157], v[180:183], v[56:59]
	v_mfma_f32_16x16x32_bf16 v[52:55], v[172:175], v[180:183], v[52:55]
	v_mfma_f32_16x16x32_bf16 v[40:43], v[154:157], v[190:193], v[40:43]
	v_mfma_f32_16x16x32_bf16 v[36:39], v[172:175], v[190:193], v[36:39]
	v_mfma_f32_16x16x32_bf16 v[24:27], v[154:157], v[198:201], v[24:27]
	v_mfma_f32_16x16x32_bf16 v[20:23], v[172:175], v[198:201], v[20:23]
	v_mfma_f32_16x16x32_bf16 v[8:11], v[154:157], v[206:209], v[8:11]
	v_mfma_f32_16x16x32_bf16 v[4:7], v[172:175], v[206:209], v[4:7]
	s_setprio 0
	s_barrier
	s_add_i32 s75, s75, 2
	s_add_u32 s55, s55, 0x100
	s_addc_u32 s74, s74, 0
	s_cmpk_gt_u32 s75, 0x55
	s_mov_b64 s[16:17], s[18:19]
	s_cbranch_scc1 .LBB0_45
	s_branch .LBB0_43

; #define PG8_STAGE(bufoff, gbase, voff) do { _Pragma("unroll") for (int _i = 0; _i < 2; ++_i) \
;         __builtin_amdgcn_global_load_lds((const unsigned*)((const char*)(gbase) + (voff)[_i]), (PG8_LAS unsigned*)(lds + (bufoff) + ldsw + _i * 8192), 16, 0, 0); } while (0)
; #define PG8_LDA(dst, b, h) do { _Pragma("unroll") for (int m = 0; m < 4; ++m) _Pragma("unroll") for (int k = 0; k < 2; ++k) dst[m][k] = *(const PG8_LAS bf16x8*)(lds + PG8_SA(b, h) + aoff + m * 2048 + k * 1024); } while (0)
; #define PG8_LDB(dst, b, h) do { _Pragma("unroll") for (int n = 0; n < 2; ++n) _Pragma("unroll") for (int k = 0; k < 2; ++k) dst[n][k] = *(const PG8_LAS bf16x8*)(lds + PG8_SB(b, h) + boff + n * 2048 + k * 1024); } while (0)
; #define PG8_WAIT_V(n) asm volatile("s_waitcnt vmcnt(" #n ")" ::: "memory")
; template <class Epi, class Sched, bool ALIGN_EPI = false, bool SP2 = false>
; __device__ __forceinline__ void gemm_phase(PG8_LAS unsigned char* lds, const Gemm g, const Sched& S, const Epi& E, const int tid) {
;     ...
;         const char* nA = has_next ? (const char*)g.A + (size_t)nxt.pm * tstep : cA; const char* nB = has_next ? (const char*)g.Bt + (size_t)nxt.pn * tstep : cB;
;         for (int t = 0; t < nt; t += 2) {
;             const bool last = (t == nt - 2);
;             const char* a1 = cA + (size_t)(t + 1) * kstep;
;             const char* a2 = last ? nA : cA + (size_t)(t + 2) * kstep; const char* b2 = last ? nB : cB + (size_t)(t + 2) * kstep;
;             const char* a3 = a2 + kstep; const char* b3 = b2 + kstep;
;             if (last && has_next) S.a_ready(nxt);
;             if (last) E.prefetch(lds + EPI_LDS_OFF + wid * 1024, cur, wr, wc, lane);
;             if constexpr (SP2) {
;             PG8_LDB(B0, 0, 0); PG8_LDB(B1, 0, 1); PG8_SCHED; PG8_LDA(At, 0, 0); PG8_STAGE(PG8_SA(1, 1), a1 + hstep, voffA);
;             PG8_WAIT_V(8); PG8_WAIT_L(0); PG8_BAR; PG8_MMA(0, 0, At, B0); PG8_MMA(0, 1, At, B1); PG8_BAR; PG8_SCHED;
;             PG8_LDA(At, 0, 1); PG8_STAGE(PG8_SB(0, 0), b2, voffB); PG8_STAGE(PG8_SB(0, 1), b2 + hstep, voffB); PG8_STAGE(PG8_SA(0, 0), a2, voffA);
;     __device__ __forceinline__ void prefetch(LAS unsigned char* sl, const pg8::Unit& u, int wr, int wc, int lane) const {
;     ...
;         const int col = u.pn * pg8::BM + wc * 32 + (lane & 31) + (lane >> 5) * pg8::HALF; const size_t bo = (size_t)(u.pm / (SEQ / 256)) * MODW;
.LBB0_227:
	s_lshl_b32 s71, s22, 8
	s_ashr_i32 s22, s63, 31
	s_lshr_b32 s22, s22, 27
	s_add_i32 s22, s63, s22
	v_or_b32_e32 v6, s71, v222
	s_ashr_i32 s22, s22, 5
	s_mul_hi_i32 s23, s22, 0x4800
	s_mulk_i32 s22, 0x4800
	v_ashrrev_i32_e32 v7, 31, v6
	s_add_u32 s74, s18, 0x100
	s_addc_u32 s75, s19, 0
	s_mov_b32 s84, -2
	s_lshl_b64 s[18:19], s[22:23], 2
	v_lshlrev_b64 v[132:133], 2, v[6:7]
	s_waitcnt vmcnt(0)
	s_mov_b64 s[24:25], 0
.Ld1_peel:
	s_add_u32 s22, s20, 0x100
	s_addc_u32 s23, s21, 0
	s_and_b64 s[24:25], s[24:25], exec
	s_cselect_b32 s27, s11, s23
	s_cselect_b32 s26, s10, s22
	s_cselect_b32 s25, s17, s75
	s_cselect_b32 s24, s16, s74
	s_add_i32 s42, 0, 0x10000
	s_add_i32 s43, 0, 0x14000
	v_add_u32_e32 v146, s42, v220
	v_add_u32_e32 v162, s43, v220
	ds_read_b128 v[134:137], v146
	ds_read_b128 v[138:141], v146 offset:1024
	ds_read_b128 v[142:145], v146 offset:2048
	ds_read_b128 v[146:149], v146 offset:3072
	ds_read_b128 v[150:153], v162
	ds_read_b128 v[154:157], v162 offset:1024
	ds_read_b128 v[158:161], v162 offset:2048
	ds_read_b128 v[172:175], v162 offset:3072
	v_lshl_add_u64 v[162:163], s[20:21], 0, v[168:169]
	s_add_i32 m0, s30, 0xc000
	ds_read_b128 v[176:179], v226
	ds_read_b128 v[186:189], v226 offset:1024
	ds_read_b128 v[190:193], v226 offset:2048
	ds_read_b128 v[194:197], v226 offset:3072
	ds_read_b128 v[198:201], v226 offset:4096
	ds_read_b128 v[202:205], v226 offset:5120
	ds_read_b128 v[206:209], v226 offset:6144
	ds_read_b128 v[210:213], v226 offset:7168
	global_load_lds_dwordx4 v[162:163], off
	v_lshl_add_u64 v[162:163], s[20:21], 0, v[170:171]
	s_add_i32 m0, s30, 0xe000
	s_nop 0
	global_load_lds_dwordx4 v[162:163], off
	s_waitcnt vmcnt(8)
	s_waitcnt lgkmcnt(0)
	s_setprio 1
	s_barrier
	v_mfma_f32_16x16x32_bf16 v[128:131], v[134:137], v[176:179], 0
	v_mfma_f32_16x16x32_bf16 v[124:127], v[142:145], v[176:179], 0
	v_mfma_f32_16x16x32_bf16 v[112:115], v[134:137], v[190:193], 0
	v_mfma_f32_16x16x32_bf16 v[108:111], v[142:145], v[190:193], 0
	v_mfma_f32_16x16x32_bf16 v[96:99], v[134:137], v[198:201], 0
	v_mfma_f32_16x16x32_bf16 v[92:95], v[142:145], v[198:201], 0
	v_mfma_f32_16x16x32_bf16 v[80:83], v[134:137], v[206:209], 0
	v_mfma_f32_16x16x32_bf16 v[76:79], v[142:145], v[206:209], 0
	v_mfma_f32_16x16x32_bf16 v[128:131], v[138:141], v[186:189], v[128:131]
	v_mfma_f32_16x16x32_bf16 v[124:127], v[146:149], v[186:189], v[124:127]
	v_mfma_f32_16x16x32_bf16 v[112:115], v[138:141], v[194:197], v[112:115]
	v_mfma_f32_16x16x32_bf16 v[108:111], v[146:149], v[194:197], v[108:111]
	v_mfma_f32_16x16x32_bf16 v[96:99], v[138:141], v[202:205], v[96:99]
	v_mfma_f32_16x16x32_bf16 v[92:95], v[146:149], v[202:205], v[92:95]
	v_mfma_f32_16x16x32_bf16 v[80:83], v[138:141], v[210:213], v[80:83]
	v_mfma_f32_16x16x32_bf16 v[76:79], v[146:149], v[210:213], v[76:79]
	s_setprio 0
	s_setprio 1
	v_mfma_f32_16x16x32_bf16 v[120:123], v[150:153], v[176:179], 0
	v_mfma_f32_16x16x32_bf16 v[116:119], v[158:161], v[176:179], 0
	v_mfma_f32_16x16x32_bf16 v[104:107], v[150:153], v[190:193], 0
	v_mfma_f32_16x16x32_bf16 v[100:103], v[158:161], v[190:193], 0
	v_mfma_f32_16x16x32_bf16 v[88:91], v[150:153], v[198:201], 0
	v_mfma_f32_16x16x32_bf16 v[84:87], v[158:161], v[198:201], 0
	v_mfma_f32_16x16x32_bf16 v[72:75], v[150:153], v[206:209], 0
	v_mfma_f32_16x16x32_bf16 v[68:71], v[158:161], v[206:209], 0
	v_mfma_f32_16x16x32_bf16 v[120:123], v[154:157], v[186:189], v[120:123]
	v_mfma_f32_16x16x32_bf16 v[116:119], v[172:175], v[186:189], v[116:119]
	v_mfma_f32_16x16x32_bf16 v[104:107], v[154:157], v[194:197], v[104:107]
	v_mfma_f32_16x16x32_bf16 v[100:103], v[172:175], v[194:197], v[100:103]
	v_mfma_f32_16x16x32_bf16 v[88:91], v[154:157], v[202:205], v[88:91]
	v_mfma_f32_16x16x32_bf16 v[84:87], v[172:175], v[202:205], v[84:87]
	v_mfma_f32_16x16x32_bf16 v[72:75], v[154:157], v[210:213], v[72:75]
	v_mfma_f32_16x16x32_bf16 v[68:71], v[172:175], v[210:213], v[68:71]
	s_setprio 0
	s_barrier
	s_add_i32 s20, s42, s29
	v_lshl_add_u64 v[162:163], s[24:25], 0, v[2:3]
	s_mov_b32 m0, s20
	ds_read_b128 v[176:179], v226 offset:16384
	ds_read_b128 v[186:189], v226 offset:17408
	ds_read_b128 v[190:193], v226 offset:18432
	ds_read_b128 v[194:197], v226 offset:19456
	ds_read_b128 v[198:201], v226 offset:20480
	ds_read_b128 v[202:205], v226 offset:21504
	ds_read_b128 v[206:209], v226 offset:22528
	ds_read_b128 v[210:213], v226 offset:23552
	global_load_lds_dwordx4 v[162:163], off
	s_add_i32 m0, s20, 0x2000
	s_add_u32 s20, s24, 0x160000
	v_lshl_add_u64 v[180:181], s[24:25], 0, v[166:167]
	s_addc_u32 s21, s25, 0
	s_add_i32 s42, s43, s29
	global_load_lds_dwordx4 v[180:181], off
	v_lshl_add_u64 v[182:183], s[20:21], 0, v[2:3]
	s_mov_b32 m0, s42
	v_lshl_add_u64 v[214:215], s[26:27], 0, v[164:165]
	global_load_lds_dwordx4 v[182:183], off
	v_lshl_add_u64 v[182:183], s[20:21], 0, v[166:167]
	s_add_i32 m0, s42, 0x2000
	s_nop 0
	global_load_lds_dwordx4 v[182:183], off
	v_lshl_add_u64 v[182:183], s[26:27], 0, v[0:1]
	s_mov_b32 m0, s30
	s_nop 0
	global_load_lds_dwordx4 v[182:183], off
	s_mov_b32 m0, s31
	s_nop 0
	global_load_lds_dwordx4 v[214:215], off
	s_waitcnt vmcnt(8)
	s_waitcnt lgkmcnt(0)
	s_setprio 1
	s_barrier
; #define PG8_STAGE(bufoff, gbase, voff) do { _Pragma("unroll") for (int _i = 0; _i < 2; ++_i) \
;         __builtin_amdgcn_global_load_lds((const unsigned*)((const char*)(gbase) + (voff)[_i]), (PG8_LAS unsigned*)(lds + (bufoff) + ldsw + _i * 8192), 16, 0, 0); } while (0)
; #define PG8_LDA(dst, b, h) do { _Pragma("unroll") for (int m = 0; m < 4; ++m) _Pragma("unroll") for (int k = 0; k < 2; ++k) dst[m][k] = *(const PG8_LAS bf16x8*)(lds + PG8_SA(b, h) + aoff + m * 2048 + k * 1024); } while (0)
; #define PG8_LDB(dst, b, h) do { _Pragma("unroll") for (int n = 0; n < 2; ++n) _Pragma("unroll") for (int k = 0; k < 2; ++k) dst[n][k] = *(const PG8_LAS bf16x8*)(lds + PG8_SB(b, h) + boff + n * 2048 + k * 1024); } while (0)
; #define PG8_MMA(ai, bj, At, Bt) do { __builtin_amdgcn_s_setprio(1); _Pragma("unroll") for (int m = 0; m < 4; ++m) _Pragma("unroll") for (int n = 0; n < 2; ++n) _Pragma("unroll") for (int k = 0; k < 2; ++k) \
;         acc[ai][bj][m][n] = __builtin_amdgcn_mfma_f32_16x16x32_bf16(Bt[n][k], At[m][k], acc[ai][bj][m][n], 0, 0, 0); __builtin_amdgcn_s_setprio(0); } while (0)
; #define PG8_WAIT_V(n) asm volatile("s_waitcnt vmcnt(" #n ")" ::: "memory")
; #define PG8_WAIT_L(n) asm volatile("s_waitcnt lgkmcnt(" #n ")" ::: "memory")
; #define PG8_BAR __builtin_amdgcn_s_barrier()
; #define PG8_SCHED __builtin_amdgcn_sched_barrier(0)
; template <class Epi, class Sched, bool ALIGN_EPI = false, bool SP2 = false>
; __device__ __forceinline__ void gemm_phase(PG8_LAS unsigned char* lds, const Gemm g, const Sched& S, const Epi& E, const int tid) {
;     ...
;             PG8_WAIT_V(8); PG8_WAIT_L(0); PG8_BAR; PG8_MMA(1, 0, At, B0); PG8_MMA(1, 1, At, B1); PG8_BAR; PG8_SCHED;
;             PG8_LDB(B0, 1, 0); PG8_LDB(B1, 1, 1); PG8_SCHED; PG8_LDA(At, 1, 0); PG8_STAGE(PG8_SA(0, 1), a2 + hstep, voffA);
;             PG8_WAIT_V(8); PG8_WAIT_L(0); PG8_BAR; PG8_MMA(0, 0, At, B0); PG8_MMA(0, 1, At, B1); PG8_BAR; PG8_SCHED;
	v_mfma_f32_16x16x32_bf16 v[64:67], v[134:137], v[176:179], 0
	v_mfma_f32_16x16x32_bf16 v[60:63], v[142:145], v[176:179], 0
	v_mfma_f32_16x16x32_bf16 v[48:51], v[134:137], v[190:193], 0
	v_mfma_f32_16x16x32_bf16 v[44:47], v[142:145], v[190:193], 0
	v_mfma_f32_16x16x32_bf16 v[32:35], v[134:137], v[198:201], 0
	v_mfma_f32_16x16x32_bf16 v[28:31], v[142:145], v[198:201], 0
	v_mfma_f32_16x16x32_bf16 v[16:19], v[134:137], v[206:209], 0
	v_mfma_f32_16x16x32_bf16 v[12:15], v[142:145], v[206:209], 0
	v_mfma_f32_16x16x32_bf16 v[64:67], v[138:141], v[186:189], v[64:67]
	v_mfma_f32_16x16x32_bf16 v[60:63], v[146:149], v[186:189], v[60:63]
	v_mfma_f32_16x16x32_bf16 v[48:51], v[138:141], v[194:197], v[48:51]
	v_mfma_f32_16x16x32_bf16 v[44:47], v[146:149], v[194:197], v[44:47]
	v_mfma_f32_16x16x32_bf16 v[32:35], v[138:141], v[202:205], v[32:35]
	v_mfma_f32_16x16x32_bf16 v[28:31], v[146:149], v[202:205], v[28:31]
	v_mfma_f32_16x16x32_bf16 v[16:19], v[138:141], v[210:213], v[16:19]
	v_mfma_f32_16x16x32_bf16 v[12:15], v[146:149], v[210:213], v[12:15]
	s_setprio 0
	s_setprio 1
	v_mfma_f32_16x16x32_bf16 v[56:59], v[150:153], v[176:179], 0
	v_mfma_f32_16x16x32_bf16 v[52:55], v[158:161], v[176:179], 0
	v_mfma_f32_16x16x32_bf16 v[40:43], v[150:153], v[190:193], 0
	v_mfma_f32_16x16x32_bf16 v[36:39], v[158:161], v[190:193], 0
	v_mfma_f32_16x16x32_bf16 v[24:27], v[150:153], v[198:201], 0
	v_mfma_f32_16x16x32_bf16 v[20:23], v[158:161], v[198:201], 0
	v_mfma_f32_16x16x32_bf16 v[8:11], v[150:153], v[206:209], 0
	v_mfma_f32_16x16x32_bf16 v[4:7], v[158:161], v[206:209], 0
	v_mfma_f32_16x16x32_bf16 v[56:59], v[154:157], v[186:189], v[56:59]
	v_mfma_f32_16x16x32_bf16 v[52:55], v[172:175], v[186:189], v[52:55]
	v_mfma_f32_16x16x32_bf16 v[40:43], v[154:157], v[194:197], v[40:43]
	v_mfma_f32_16x16x32_bf16 v[36:39], v[172:175], v[194:197], v[36:39]
	v_mfma_f32_16x16x32_bf16 v[24:27], v[154:157], v[202:205], v[24:27]
	v_mfma_f32_16x16x32_bf16 v[20:23], v[172:175], v[202:205], v[20:23]
	v_mfma_f32_16x16x32_bf16 v[8:11], v[154:157], v[210:213], v[8:11]
	v_mfma_f32_16x16x32_bf16 v[4:7], v[172:175], v[210:213], v[4:7]
	s_setprio 0
	s_barrier
	s_add_i32 s42, 0, 0x18000
	s_add_i32 s43, 0, 0x1c000
	v_add_u32_e32 v146, s42, v220
	v_add_u32_e32 v172, s43, v220
	ds_read_b128 v[134:137], v146
	ds_read_b128 v[138:141], v146 offset:1024
	ds_read_b128 v[142:145], v146 offset:2048
	ds_read_b128 v[146:149], v146 offset:3072
	ds_read_b128 v[150:153], v172
	ds_read_b128 v[154:157], v172 offset:1024
	ds_read_b128 v[158:161], v172 offset:2048
	ds_read_b128 v[172:175], v172 offset:3072
	s_add_u32 s20, s26, 0x160000
	s_addc_u32 s21, s27, 0
	s_mov_b32 m0, s36
	v_lshl_add_u64 v[216:217], s[20:21], 0, v[0:1]
	ds_read_b128 v[176:179], v226 offset:32768
	ds_read_b128 v[186:189], v226 offset:33792
	ds_read_b128 v[190:193], v226 offset:34816
	ds_read_b128 v[194:197], v226 offset:35840
	ds_read_b128 v[198:201], v226 offset:36864
	ds_read_b128 v[202:205], v226 offset:37888
	ds_read_b128 v[206:209], v226 offset:38912
	ds_read_b128 v[210:213], v226 offset:39936
	global_load_lds_dwordx4 v[216:217], off
	v_lshl_add_u64 v[216:217], s[20:21], 0, v[164:165]
	s_mov_b32 m0, s37
	s_nop 0
	global_load_lds_dwordx4 v[216:217], off
	s_waitcnt vmcnt(8)
	s_waitcnt lgkmcnt(0)
	s_setprio 1
	s_barrier
	v_mfma_f32_16x16x32_bf16 v[128:131], v[134:137], v[176:179], v[128:131]
	v_mfma_f32_16x16x32_bf16 v[124:127], v[142:145], v[176:179], v[124:127]
	v_mfma_f32_16x16x32_bf16 v[112:115], v[134:137], v[190:193], v[112:115]
	v_mfma_f32_16x16x32_bf16 v[108:111], v[142:145], v[190:193], v[108:111]
	v_mfma_f32_16x16x32_bf16 v[96:99], v[134:137], v[198:201], v[96:99]
	v_mfma_f32_16x16x32_bf16 v[92:95], v[142:145], v[198:201], v[92:95]
	v_mfma_f32_16x16x32_bf16 v[80:83], v[134:137], v[206:209], v[80:83]
	v_mfma_f32_16x16x32_bf16 v[76:79], v[142:145], v[206:209], v[76:79]
	v_mfma_f32_16x16x32_bf16 v[128:131], v[138:141], v[186:189], v[128:131]
	v_mfma_f32_16x16x32_bf16 v[124:127], v[146:149], v[186:189], v[124:127]
	v_mfma_f32_16x16x32_bf16 v[112:115], v[138:141], v[194:197], v[112:115]
	v_mfma_f32_16x16x32_bf16 v[108:111], v[146:149], v[194:197], v[108:111]
	v_mfma_f32_16x16x32_bf16 v[96:99], v[138:141], v[202:205], v[96:99]
	v_mfma_f32_16x16x32_bf16 v[92:95], v[146:149], v[202:205], v[92:95]
	v_mfma_f32_16x16x32_bf16 v[80:83], v[138:141], v[210:213], v[80:83]
	v_mfma_f32_16x16x32_bf16 v[76:79], v[146:149], v[210:213], v[76:79]
	s_setprio 0
	s_setprio 1
	v_mfma_f32_16x16x32_bf16 v[120:123], v[150:153], v[176:179], v[120:123]
	v_mfma_f32_16x16x32_bf16 v[116:119], v[158:161], v[176:179], v[116:119]
	v_mfma_f32_16x16x32_bf16 v[104:107], v[150:153], v[190:193], v[104:107]
	v_mfma_f32_16x16x32_bf16 v[100:103], v[158:161], v[190:193], v[100:103]
	v_mfma_f32_16x16x32_bf16 v[88:91], v[150:153], v[198:201], v[88:91]
	v_mfma_f32_16x16x32_bf16 v[84:87], v[158:161], v[198:201], v[84:87]
	v_mfma_f32_16x16x32_bf16 v[72:75], v[150:153], v[206:209], v[72:75]
	v_mfma_f32_16x16x32_bf16 v[68:71], v[158:161], v[206:209], v[68:71]
	v_mfma_f32_16x16x32_bf16 v[120:123], v[154:157], v[186:189], v[120:123]
	v_mfma_f32_16x16x32_bf16 v[116:119], v[172:175], v[186:189], v[116:119]
	v_mfma_f32_16x16x32_bf16 v[104:107], v[154:157], v[194:197], v[104:107]
	v_mfma_f32_16x16x32_bf16 v[100:103], v[172:175], v[194:197], v[100:103]
	v_mfma_f32_16x16x32_bf16 v[88:91], v[154:157], v[202:205], v[88:91]
	v_mfma_f32_16x16x32_bf16 v[84:87], v[172:175], v[202:205], v[84:87]
	v_mfma_f32_16x16x32_bf16 v[72:75], v[154:157], v[210:213], v[72:75]
	v_mfma_f32_16x16x32_bf16 v[68:71], v[172:175], v[210:213], v[68:71]
	s_setprio 0
	s_barrier
; #define PG8_STAGE(bufoff, gbase, voff) do { _Pragma("unroll") for (int _i = 0; _i < 2; ++_i) \
;         __builtin_amdgcn_global_load_lds((const unsigned*)((const char*)(gbase) + (voff)[_i]), (PG8_LAS unsigned*)(lds + (bufoff) + ldsw + _i * 8192), 16, 0, 0); } while (0)
; #define PG8_LDA(dst, b, h) do { _Pragma("unroll") for (int m = 0; m < 4; ++m) _Pragma("unroll") for (int k = 0; k < 2; ++k) dst[m][k] = *(const PG8_LAS bf16x8*)(lds + PG8_SA(b, h) + aoff + m * 2048 + k * 1024); } while (0)
; #define PG8_MMA(ai, bj, At, Bt) do { __builtin_amdgcn_s_setprio(1); _Pragma("unroll") for (int m = 0; m < 4; ++m) _Pragma("unroll") for (int n = 0; n < 2; ++n) _Pragma("unroll") for (int k = 0; k < 2; ++k) \
;         acc[ai][bj][m][n] = __builtin_amdgcn_mfma_f32_16x16x32_bf16(Bt[n][k], At[m][k], acc[ai][bj][m][n], 0, 0, 0); __builtin_amdgcn_s_setprio(0); } while (0)
; #define PG8_WAIT_V(n) asm volatile("s_waitcnt vmcnt(" #n ")" ::: "memory")
; #define PG8_WAIT_L(n) asm volatile("s_waitcnt lgkmcnt(" #n ")" ::: "memory")
; #define PG8_BAR __builtin_amdgcn_s_barrier()
; #define PG8_SCHED __builtin_amdgcn_sched_barrier(0)
; template <class Epi, class Sched, bool ALIGN_EPI = false, bool SP2 = false>
; __device__ __forceinline__ void gemm_phase(PG8_LAS unsigned char* lds, const Gemm g, const Sched& S, const Epi& E, const int tid) {
;     ...
;         for (int t = 0; t < nt; t += 2) {
;     ...
;             PG8_LDA(At, 1, 1); PG8_STAGE(PG8_SB(1, 0), b3, voffB); PG8_STAGE(PG8_SB(1, 1), b3 + hstep, voffB); PG8_STAGE(PG8_SA(1, 0), a3, voffA);
;             PG8_WAIT_V(8); PG8_WAIT_L(0); PG8_BAR; PG8_MMA(1, 0, At, B0); PG8_MMA(1, 1, At, B1); PG8_BAR; PG8_SCHED;
	s_add_i32 s20, s42, s29
	v_lshl_add_u64 v[162:163], v[162:163], 0, s[46:47]
	s_mov_b32 m0, s20
	ds_read_b128 v[176:179], v226 offset:49152
	ds_read_b128 v[186:189], v226 offset:50176
	ds_read_b128 v[190:193], v226 offset:51200
	ds_read_b128 v[194:197], v226 offset:52224
	ds_read_b128 v[198:201], v226 offset:53248
	ds_read_b128 v[202:205], v226 offset:54272
	ds_read_b128 v[206:209], v226 offset:55296
	ds_read_b128 v[210:213], v226 offset:56320
	global_load_lds_dwordx4 v[162:163], off
	s_add_i32 m0, s20, 0x2000
	s_add_u32 s20, s24, 0x160080
	v_lshl_add_u64 v[162:163], v[180:181], 0, s[46:47]
	s_addc_u32 s21, s25, 0
	s_add_i32 s24, s43, s29
	global_load_lds_dwordx4 v[162:163], off
	v_lshl_add_u64 v[162:163], s[20:21], 0, v[2:3]
	s_mov_b32 m0, s24
	s_nop 0
	global_load_lds_dwordx4 v[162:163], off
	v_lshl_add_u64 v[162:163], s[20:21], 0, v[166:167]
	s_add_i32 m0, s24, 0x2000
	s_nop 0
	global_load_lds_dwordx4 v[162:163], off
	v_lshl_add_u64 v[162:163], v[182:183], 0, s[46:47]
	s_mov_b32 m0, s39
	s_nop 0
	global_load_lds_dwordx4 v[162:163], off
	v_lshl_add_u64 v[162:163], v[214:215], 0, s[46:47]
	s_mov_b32 m0, s44
	s_nop 0
	global_load_lds_dwordx4 v[162:163], off
	s_waitcnt vmcnt(8)
	s_waitcnt lgkmcnt(0)
	s_setprio 1
	s_barrier
	v_mfma_f32_16x16x32_bf16 v[64:67], v[134:137], v[176:179], v[64:67]
	v_mfma_f32_16x16x32_bf16 v[60:63], v[142:145], v[176:179], v[60:63]
	v_mfma_f32_16x16x32_bf16 v[48:51], v[134:137], v[190:193], v[48:51]
	v_mfma_f32_16x16x32_bf16 v[44:47], v[142:145], v[190:193], v[44:47]
	v_mfma_f32_16x16x32_bf16 v[32:35], v[134:137], v[198:201], v[32:35]
	v_mfma_f32_16x16x32_bf16 v[28:31], v[142:145], v[198:201], v[28:31]
	v_mfma_f32_16x16x32_bf16 v[16:19], v[134:137], v[206:209], v[16:19]
	v_mfma_f32_16x16x32_bf16 v[12:15], v[142:145], v[206:209], v[12:15]
	v_mfma_f32_16x16x32_bf16 v[64:67], v[138:141], v[186:189], v[64:67]
	v_mfma_f32_16x16x32_bf16 v[60:63], v[146:149], v[186:189], v[60:63]
	v_mfma_f32_16x16x32_bf16 v[48:51], v[138:141], v[194:197], v[48:51]
	v_mfma_f32_16x16x32_bf16 v[44:47], v[146:149], v[194:197], v[44:47]
	v_mfma_f32_16x16x32_bf16 v[32:35], v[138:141], v[202:205], v[32:35]
	v_mfma_f32_16x16x32_bf16 v[28:31], v[146:149], v[202:205], v[28:31]
	v_mfma_f32_16x16x32_bf16 v[16:19], v[138:141], v[210:213], v[16:19]
	v_mfma_f32_16x16x32_bf16 v[12:15], v[146:149], v[210:213], v[12:15]
	s_setprio 0
	s_setprio 1
	v_mfma_f32_16x16x32_bf16 v[56:59], v[150:153], v[176:179], v[56:59]
	v_mfma_f32_16x16x32_bf16 v[52:55], v[158:161], v[176:179], v[52:55]
	v_mfma_f32_16x16x32_bf16 v[40:43], v[150:153], v[190:193], v[40:43]
	v_mfma_f32_16x16x32_bf16 v[36:39], v[158:161], v[190:193], v[36:39]
	v_mfma_f32_16x16x32_bf16 v[24:27], v[150:153], v[198:201], v[24:27]
	v_mfma_f32_16x16x32_bf16 v[20:23], v[158:161], v[198:201], v[20:23]
	v_mfma_f32_16x16x32_bf16 v[8:11], v[150:153], v[206:209], v[8:11]
	v_mfma_f32_16x16x32_bf16 v[4:7], v[158:161], v[206:209], v[4:7]
	v_mfma_f32_16x16x32_bf16 v[56:59], v[154:157], v[186:189], v[56:59]
	v_mfma_f32_16x16x32_bf16 v[52:55], v[172:175], v[186:189], v[52:55]
	v_mfma_f32_16x16x32_bf16 v[40:43], v[154:157], v[194:197], v[40:43]
	v_mfma_f32_16x16x32_bf16 v[36:39], v[172:175], v[194:197], v[36:39]
	v_mfma_f32_16x16x32_bf16 v[24:27], v[154:157], v[202:205], v[24:27]
	v_mfma_f32_16x16x32_bf16 v[20:23], v[172:175], v[202:205], v[20:23]
	v_mfma_f32_16x16x32_bf16 v[8:11], v[154:157], v[210:213], v[8:11]
	v_mfma_f32_16x16x32_bf16 v[4:7], v[172:175], v[210:213], v[4:7]
	s_setprio 0
	s_barrier
	s_add_i32 s84, s84, 2
	s_add_u32 s74, s74, 0x100
	s_addc_u32 s75, s75, 0
	s_cmpk_gt_u32 s84, 0x55
	s_mov_b64 s[20:21], s[22:23]
	s_cbranch_scc1 .LBB0_231
	s_branch .LBB0_229
